# residual epilogue lane-coalesced: accumulator slabs re-laid through a private LDS patch so consecutive lanes access consecutive 16-byte chunks (8 lanes per 128-B line)
# speedup vs baseline: 1.0082x; 1.0049x over previous
; #define FOR_AI_M _Pragma("unroll") for (int ai = 0; ai < 2; ++ai) _Pragma("unroll") for (int m = 0; m < 4; ++m)
;     __device__ __forceinline__ void operator()(const f32x4 (&acc)[2][2][4][2], const Unit& u, int wr, int wc, int fr, int fq) const {
;         const int row0 = 256 * u.pm; const bool isctx = row0 >= NLAT; const int mb = isctx ? 4 : (row0 >> 13);
;         const float* bp = isctx ? base_ctx + (size_t)(row0 - NLAT) * 1024 : base_lat + (size_t)row0 * 1024;
;         float* op = isctx ? out_ctx + (size_t)(row0 - NLAT) * 1024 : out_lat + (size_t)row0 * 1024;
;         const float* mp = mod + mb * 6144 + moff;
;         f32x4 mv[2][2];
; #pragma unroll
;         for (int bj = 0; bj < 2; ++bj)
; #pragma unroll
;             for (int n = 0; n < 2; ++n) mv[bj][n] = *(const f32x4*)(mp + 256 * u.pn + 128 * bj + 32 * wc + 8 * fq + 4 * n);
;         const size_t cb0 = (size_t)256 * u.pn + 32 * wc + 8 * fq;
;         if (u.mode > 0) {
;             float* pp = part + (size_t)(u.mode - 1) * NCTX * 1024 + (size_t)(row0 - NLAT) * 1024;
;             FOR_AI_M {
;                 const size_t ro = (size_t)(128 * ai + 64 * wr + 16 * m + fr) * 1024 + cb0;
; #pragma unroll
;                 for (int bj = 0; bj < 2; ++bj)
; #pragma unroll
;                     for (int n = 0; n < 2; ++n) *(f32x4*)(pp + ro + 128 * bj + 4 * n) = mv[bj][n] * acc[ai][bj][m][n];
;             }
;             return;
;         }
;         f32x4 pre[2][2][2];
; #pragma unroll
;         for (int bj = 0; bj < 2; ++bj)
; #pragma unroll
;             for (int n = 0; n < 2; ++n) pre[0][bj][n] = *(const f32x4*)(bp + (size_t)(64 * wr + fr) * 1024 + cb0 + 128 * bj + 4 * n);
.LBB0_67:
	s_min_i32 s2, s96, 0x80
	s_lshr_b32 s2, s2, 5
	s_mulk_i32 s2, 0x1800
	s_ashr_i32 s3, s2, 31
	s_lshl_b32 s18, s96, 8
	s_lshl_b64 s[2:3], s[2:3], 2
	v_readlane_b32 s8, v254, 44
	s_add_u32 s17, s8, s2
	v_readlane_b32 s2, v254, 46
	s_addc_u32 s19, s2, s3
	s_lshl_b32 s2, s16, 8
	s_ashr_i32 s3, s2, 31
	s_lshl_b64 s[2:3], s[2:3], 2
	s_add_u32 s2, s17, s2
	v_mov_b32_e32 v128, v191
	v_mov_b32_e32 v146, v190
	s_addc_u32 s3, s19, s3
	v_readlane_b32 s8, v255, 3
	s_add_u32 s2, s2, s8
	v_lshlrev_b32_e32 v144, 3, v128
	s_addc_u32 s3, s3, 0
	v_ashrrev_i32_e32 v145, 31, v144
	v_lshl_add_u64 v[128:129], v[144:145], 2, s[2:3]
	s_mov_b64 s[2:3], 0x5000
	v_lshl_add_u64 v[130:131], v[128:129], 0, s[2:3]
	s_movk_i32 s2, 0x5000
	v_add_co_u32_e32 v128, vcc, s2, v128
	s_ashr_i32 s17, s16, 31
	s_nop 0
	v_addc_co_u32_e32 v129, vcc, 0, v129, vcc
	global_load_dwordx4 v[136:139], v[130:131], off offset:16
	global_load_dwordx4 v[132:135], v[130:131], off offset:512
	global_load_dwordx4 v[140:143], v[128:129], off
	s_nop 0
	global_load_dwordx4 v[128:131], v[130:131], off offset:528
	v_readlane_b32 s8, v254, 63
	s_lshl_b64 s[2:3], s[16:17], 8
	v_readlane_b32 s9, v255, 0
	s_or_b64 s[2:3], s[2:3], s[8:9]
	v_lshl_add_u64 v[182:183], s[2:3], 0, v[144:145]
	v_readlane_b32 s2, v254, 61
	s_cmp_lt_i32 s64, 1
	s_mov_b64 s[16:17], -1
	v_add_u32_e32 v180, s2, v146
	v_add_u32_e32 v178, 16, v180
	v_add_u32_e32 v176, 32, v180
	v_add_u32_e32 v174, 48, v180
	v_add_u32_e32 v172, 0x80, v180
	v_add_u32_e32 v170, 0x90, v180
	v_ashrrev_i32_e32 v181, 31, v180
	v_ashrrev_i32_e32 v179, 31, v178
	v_ashrrev_i32_e32 v177, 31, v176
	v_ashrrev_i32_e32 v175, 31, v174
	v_ashrrev_i32_e32 v173, 31, v172
	v_ashrrev_i32_e32 v171, 31, v170
	v_add_u32_e32 v168, 0xa0, v180
	v_add_u32_e32 v166, 0xb0, v180
	s_cbranch_scc0 .LBB0_70
	s_add_i32 s2, s18, 0xffff8000
	s_ashr_i32 s3, s18, 31
	s_mov_b32 s16, s11
	s_mov_b32 s17, s10
	v_readlane_b32 s8, v251, 0
	s_cmpk_gt_i32 s96, 0x7f
	v_readlane_b32 s11, v251, 3
	v_readlane_b32 s15, v251, 7
	v_readlane_b32 s8, v254, 49
	v_readlane_b32 s10, v251, 2
	v_readlane_b32 s14, v251, 6
	s_mov_b32 s11, s16
	s_cselect_b32 s16, s8, s15
	v_readlane_b32 s8, v254, 47
	s_cselect_b32 s3, 0, s3
	s_cselect_b32 s2, s2, s18
	s_mov_b32 s10, s17
	s_cselect_b32 s17, s8, s14
	s_lshl_b64 s[2:3], s[2:3], 12
	s_add_u32 s2, s17, s2
	s_addc_u32 s3, s16, s3
	v_ashrrev_i32_e32 v181, 31, v180
	v_ashrrev_i32_e32 v179, 31, v178
	v_ashrrev_i32_e32 v177, 31, v176
	v_ashrrev_i32_e32 v175, 31, v174
	v_ashrrev_i32_e32 v173, 31, v172
	v_ashrrev_i32_e32 v171, 31, v170
	v_ashrrev_i32_e32 v169, 31, v168
	v_ashrrev_i32_e32 v167, 31, v166
	s_mov_b64 s[60:61], 0x8000
	s_mov_b64 s[62:63], -16
	s_add_i32 s58, s23, 0xc000
	v_mbcnt_lo_u32_b32 v248, -1, 0
	v_mbcnt_hi_u32_b32 v248, -1, v248
	v_lshrrev_b32_e32 v249, 4, v248
	v_and_b32_e32 v200, 7, v248
	v_xor_b32_e32 v200, v200, v249
	v_lshlrev_b32_e32 v200, 4, v200
	v_lshrrev_b32_e32 v201, 3, v248
	v_lshl_add_u32 v200, v201, 7, v200
	v_add_u32_e32 v184, s58, v200
	v_bfe_u32 v200, v248, 1, 2
	v_lshlrev_b32_e32 v201, 1, v249
	v_xor_b32_e32 v200, v200, v201
	v_lshlrev_b32_e32 v200, 4, v200
	v_and_b32_e32 v201, 7, v248
	v_lshl_add_u32 v200, v201, 7, v200
	v_bfe_u32 v201, v248, 3, 1
	v_lshl_add_u32 v200, v201, 13, v200
	v_add_u32_e32 v199, s58, v200
	v_xor_b32_e32 v247, 16, v199
	v_lshrrev_b32_e32 v200, 3, v248
	v_and_b32_e32 v201, 15, v248
	v_sub_u32_e32 v200, v200, v201
	v_lshlrev_b32_e32 v200, 12, v200
	v_and_b32_e32 v201, 7, v248
	v_lshl_add_u32 v200, v201, 4, v200
	v_lshlrev_b32_e32 v201, 5, v249
	v_sub_u32_e32 v200, v200, v201
	v_ashrrev_i32_e32 v201, 31, v200
	v_lshlrev_b64 v[186:187], 2, v[182:183]
	v_lshl_add_u64 v[186:187], v[200:201], 0, v[186:187]
	v_lshl_add_u64 v[188:189], s[2:3], 0, v[186:187]
	v_lshl_add_u64 v[186:187], s[2:3], 0, v[186:187]
	v_lshlrev_b64 v[200:201], 12, v[180:181]
	v_lshl_add_u64 v[200:201], v[186:187], 0, v[200:201]
	global_load_dwordx4 v[144:147], v[200:201], off
	global_load_dwordx4 v[148:151], v[200:201], off offset:512
	v_lshl_add_u64 v[200:201], v[200:201], 0, s[60:61]
	global_load_dwordx4 v[152:155], v[200:201], off
	global_load_dwordx4 v[156:159], v[200:201], off offset:512
	v_lshlrev_b64 v[200:201], 12, v[178:179]
	v_lshl_add_u64 v[200:201], v[186:187], 0, v[200:201]
	global_load_dwordx4 v[202:205], v[200:201], off
	global_load_dwordx4 v[206:209], v[200:201], off offset:512
	v_lshl_add_u64 v[200:201], v[200:201], 0, s[60:61]
	global_load_dwordx4 v[210:213], v[200:201], off
	global_load_dwordx4 v[214:217], v[200:201], off offset:512
	v_lshlrev_b64 v[200:201], 12, v[176:177]
	v_lshl_add_u64 v[200:201], v[186:187], 0, v[200:201]
	global_load_dwordx4 v[218:221], v[200:201], off
	global_load_dwordx4 v[222:225], v[200:201], off offset:512
	v_lshl_add_u64 v[200:201], v[200:201], 0, s[60:61]
	global_load_dwordx4 v[230:233], v[200:201], off
	global_load_dwordx4 v[234:237], v[200:201], off offset:512
	ds_write_b128 v199, v[124:127]
	ds_write_b128 v247, v[120:123]
	ds_read_b128 v[124:127], v184
	ds_read_b128 v[120:123], v184 offset:8192
	ds_write_b128 v199, v[112:115]
	ds_write_b128 v247, v[104:107]
	ds_read_b128 v[112:115], v184
	ds_read_b128 v[104:107], v184 offset:8192
	s_waitcnt lgkmcnt(2)
	ds_write_b128 v199, v[116:119]
	ds_write_b128 v247, v[108:111]
	ds_read_b128 v[116:119], v184
	ds_read_b128 v[108:111], v184 offset:8192
	ds_write_b128 v199, v[96:99]
	ds_write_b128 v247, v[88:91]
	ds_read_b128 v[96:99], v184
	ds_read_b128 v[88:91], v184 offset:8192
	s_waitcnt lgkmcnt(2)
	ds_write_b128 v199, v[100:103]
	ds_write_b128 v247, v[92:95]
	ds_read_b128 v[100:103], v184
	ds_read_b128 v[92:95], v184 offset:8192
	ds_write_b128 v199, v[80:83]
	ds_write_b128 v247, v[72:75]
	ds_read_b128 v[80:83], v184
	ds_read_b128 v[72:75], v184 offset:8192
	s_waitcnt lgkmcnt(2)
;     __device__ __forceinline__ void operator()(const f32x4 (&acc)[2][2][4][2], const Unit& u, int wr, int wc, int fr, int fq) const {
;     ...
; #pragma unroll
;         for (int g = 0; g < 8; ++g) {
;             const int ai = g >> 2, m = g & 3;
;             const size_t ro = (size_t)(128 * ai + 64 * wr + 16 * m + fr) * 1024 + cb0;
;             if (g + 1 < 8) {
;                 const size_t rn = (size_t)(128 * ((g + 1) >> 2) + 64 * wr + 16 * ((g + 1) & 3) + fr) * 1024 + cb0;
; #pragma unroll
;                 for (int bj = 0; bj < 2; ++bj)
; #pragma unroll
;                     for (int n = 0; n < 2; ++n) pre[(g + 1) & 1][bj][n] = *(const f32x4*)(bp + rn + 128 * bj + 4 * n);
;             }
;             asm volatile("" ::: "memory");
; #pragma unroll
;             for (int bj = 0; bj < 2; ++bj)
; #pragma unroll
;                 for (int n = 0; n < 2; ++n) *(f32x4*)(op + ro + 128 * bj + 4 * n) = pre[g & 1][bj][n] + mv[bj][n] * acc[ai][bj][m][n];
;         }
	ds_write_b128 v199, v[84:87]
	ds_write_b128 v247, v[76:79]
	ds_read_b128 v[84:87], v184
	ds_read_b128 v[76:79], v184 offset:8192
	ds_write_b128 v199, v[68:71]
	ds_write_b128 v247, v[64:67]
	ds_read_b128 v[68:71], v184
	ds_read_b128 v[64:67], v184 offset:8192
	s_waitcnt lgkmcnt(2)
	ds_write_b128 v199, v[60:63]
	ds_write_b128 v247, v[56:59]
	ds_read_b128 v[60:63], v184
	ds_read_b128 v[56:59], v184 offset:8192
	ds_write_b128 v199, v[48:51]
	ds_write_b128 v247, v[40:43]
	ds_read_b128 v[48:51], v184
	ds_read_b128 v[40:43], v184 offset:8192
	s_waitcnt lgkmcnt(2)
	ds_write_b128 v199, v[52:55]
	ds_write_b128 v247, v[44:47]
	ds_read_b128 v[52:55], v184
	ds_read_b128 v[44:47], v184 offset:8192
	ds_write_b128 v199, v[32:35]
	ds_write_b128 v247, v[24:27]
	ds_read_b128 v[32:35], v184
	ds_read_b128 v[24:27], v184 offset:8192
	s_waitcnt lgkmcnt(2)
	ds_write_b128 v199, v[36:39]
	ds_write_b128 v247, v[28:31]
	ds_read_b128 v[36:39], v184
	ds_read_b128 v[28:31], v184 offset:8192
	ds_write_b128 v199, v[16:19]
	ds_write_b128 v247, v[8:11]
	ds_read_b128 v[16:19], v184
	ds_read_b128 v[8:11], v184 offset:8192
	s_waitcnt lgkmcnt(2)
	ds_write_b128 v199, v[20:23]
	ds_write_b128 v247, v[12:15]
	ds_read_b128 v[20:23], v184
	ds_read_b128 v[12:15], v184 offset:8192
	ds_write_b128 v199, v[4:7]
	ds_write_b128 v247, v[0:3]
	ds_read_b128 v[4:7], v184
	ds_read_b128 v[0:3], v184 offset:8192
	s_waitcnt lgkmcnt(2)
	s_waitcnt lgkmcnt(0)
	s_waitcnt vmcnt(8)
	v_mbcnt_lo_u32_b32 v201, -1, 0
	v_mbcnt_hi_u32_b32 v201, -1, v201
	v_lshrrev_b32_e32 v200, 4, v201
	v_lshl_add_u32 v200, v200, 5, s58
	v_and_b32_e32 v201, 7, v201
	v_lshl_add_u32 v201, v201, 4, s58
	ds_write_b128 v200, v[140:143]
	ds_write_b128 v200, v[136:139] offset:16
	ds_read_b128 v[140:143], v201
	ds_write_b128 v200, v[132:135]
	ds_write_b128 v200, v[128:131] offset:16
	ds_read_b128 v[132:135], v201
	s_waitcnt lgkmcnt(0)
	v_lshlrev_b64 v[248:249], 12, v[180:181]
	v_lshl_add_u64 v[248:249], v[188:189], 0, v[248:249]
	s_waitcnt vmcnt(8)
	v_pk_fma_f32 v[144:145], v[124:125], v[140:141], v[144:145]
	v_pk_fma_f32 v[146:147], v[126:127], v[142:143], v[146:147]
	v_pk_fma_f32 v[148:149], v[112:113], v[132:133], v[148:149]
	v_pk_fma_f32 v[150:151], v[114:115], v[134:135], v[150:151]
	v_pk_fma_f32 v[152:153], v[120:121], v[140:141], v[152:153]
	v_pk_fma_f32 v[154:155], v[122:123], v[142:143], v[154:155]
	v_pk_fma_f32 v[156:157], v[104:105], v[132:133], v[156:157]
	v_pk_fma_f32 v[158:159], v[106:107], v[134:135], v[158:159]
	global_store_dwordx4 v[248:249], v[144:147], off
	global_store_dwordx4 v[248:249], v[148:151], off offset:512
	v_lshl_add_u64 v[248:249], v[248:249], 0, s[60:61]
	global_store_dwordx4 v[248:249], v[152:155], off
	global_store_dwordx4 v[248:249], v[156:159], off offset:512
	v_lshlrev_b64 v[200:201], 12, v[174:175]
	v_lshl_add_u64 v[200:201], v[186:187], 0, v[200:201]
	global_load_dwordx4 v[144:147], v[200:201], off
	global_load_dwordx4 v[148:151], v[200:201], off offset:512
	v_lshl_add_u64 v[200:201], v[200:201], 0, s[60:61]
	global_load_dwordx4 v[152:155], v[200:201], off
	global_load_dwordx4 v[156:159], v[200:201], off offset:512
	v_lshlrev_b64 v[248:249], 12, v[178:179]
	v_lshl_add_u64 v[248:249], v[188:189], 0, v[248:249]
	s_waitcnt vmcnt(12)
	v_pk_fma_f32 v[202:203], v[116:117], v[140:141], v[202:203]
	v_pk_fma_f32 v[204:205], v[118:119], v[142:143], v[204:205]
	v_pk_fma_f32 v[206:207], v[96:97], v[132:133], v[206:207]
	v_pk_fma_f32 v[208:209], v[98:99], v[134:135], v[208:209]
	v_pk_fma_f32 v[210:211], v[108:109], v[140:141], v[210:211]
	v_pk_fma_f32 v[212:213], v[110:111], v[142:143], v[212:213]
	v_pk_fma_f32 v[214:215], v[88:89], v[132:133], v[214:215]
	v_pk_fma_f32 v[216:217], v[90:91], v[134:135], v[216:217]
	global_store_dwordx4 v[248:249], v[202:205], off
	global_store_dwordx4 v[248:249], v[206:209], off offset:512
	v_lshl_add_u64 v[248:249], v[248:249], 0, s[60:61]
	global_store_dwordx4 v[248:249], v[210:213], off
	global_store_dwordx4 v[248:249], v[214:217], off offset:512
	v_lshlrev_b64 v[200:201], 12, v[172:173]
	v_lshl_add_u64 v[200:201], v[186:187], 0, v[200:201]
	global_load_dwordx4 v[202:205], v[200:201], off
	global_load_dwordx4 v[206:209], v[200:201], off offset:512
	v_lshl_add_u64 v[200:201], v[200:201], 0, s[60:61]
	global_load_dwordx4 v[210:213], v[200:201], off
	global_load_dwordx4 v[214:217], v[200:201], off offset:512
	v_lshlrev_b64 v[248:249], 12, v[176:177]
	v_lshl_add_u64 v[248:249], v[188:189], 0, v[248:249]
	s_waitcnt vmcnt(16)
	v_pk_fma_f32 v[218:219], v[100:101], v[140:141], v[218:219]
	v_pk_fma_f32 v[220:221], v[102:103], v[142:143], v[220:221]
	v_pk_fma_f32 v[222:223], v[80:81], v[132:133], v[222:223]
	v_pk_fma_f32 v[224:225], v[82:83], v[134:135], v[224:225]
	v_pk_fma_f32 v[230:231], v[92:93], v[140:141], v[230:231]
	v_pk_fma_f32 v[232:233], v[94:95], v[142:143], v[232:233]
	v_pk_fma_f32 v[234:235], v[72:73], v[132:133], v[234:235]
	v_pk_fma_f32 v[236:237], v[74:75], v[134:135], v[236:237]
	global_store_dwordx4 v[248:249], v[218:221], off
	global_store_dwordx4 v[248:249], v[222:225], off offset:512
	v_lshl_add_u64 v[248:249], v[248:249], 0, s[60:61]
	global_store_dwordx4 v[248:249], v[230:233], off
	global_store_dwordx4 v[248:249], v[234:237], off offset:512
	v_lshlrev_b64 v[200:201], 12, v[170:171]
	v_lshl_add_u64 v[200:201], v[186:187], 0, v[200:201]
	global_load_dwordx4 v[218:221], v[200:201], off
	global_load_dwordx4 v[222:225], v[200:201], off offset:512
	v_lshl_add_u64 v[200:201], v[200:201], 0, s[60:61]
	global_load_dwordx4 v[230:233], v[200:201], off
	global_load_dwordx4 v[234:237], v[200:201], off offset:512
	v_lshlrev_b64 v[248:249], 12, v[174:175]
	v_lshl_add_u64 v[248:249], v[188:189], 0, v[248:249]
	s_waitcnt vmcnt(16)
;     __device__ __forceinline__ void operator()(const f32x4 (&acc)[2][2][4][2], const Unit& u, int wr, int wc, int fr, int fq) const {
;     ...
;         for (int g = 0; g < 8; ++g) {
;             const int ai = g >> 2, m = g & 3;
;             const size_t ro = (size_t)(128 * ai + 64 * wr + 16 * m + fr) * 1024 + cb0;
;             if (g + 1 < 8) {
;                 const size_t rn = (size_t)(128 * ((g + 1) >> 2) + 64 * wr + 16 * ((g + 1) & 3) + fr) * 1024 + cb0;
; #pragma unroll
;                 for (int bj = 0; bj < 2; ++bj)
; #pragma unroll
;                     for (int n = 0; n < 2; ++n) pre[(g + 1) & 1][bj][n] = *(const f32x4*)(bp + rn + 128 * bj + 4 * n);
;             }
;             asm volatile("" ::: "memory");
; #pragma unroll
;             for (int bj = 0; bj < 2; ++bj)
; #pragma unroll
;                 for (int n = 0; n < 2; ++n) *(f32x4*)(op + ro + 128 * bj + 4 * n) = pre[g & 1][bj][n] + mv[bj][n] * acc[ai][bj][m][n];
;         }
	v_pk_fma_f32 v[144:145], v[84:85], v[140:141], v[144:145]
	v_pk_fma_f32 v[146:147], v[86:87], v[142:143], v[146:147]
	v_pk_fma_f32 v[148:149], v[68:69], v[132:133], v[148:149]
	v_pk_fma_f32 v[150:151], v[70:71], v[134:135], v[150:151]
	v_pk_fma_f32 v[152:153], v[76:77], v[140:141], v[152:153]
	v_pk_fma_f32 v[154:155], v[78:79], v[142:143], v[154:155]
	v_pk_fma_f32 v[156:157], v[64:65], v[132:133], v[156:157]
	v_pk_fma_f32 v[158:159], v[66:67], v[134:135], v[158:159]
	global_store_dwordx4 v[248:249], v[144:147], off
	global_store_dwordx4 v[248:249], v[148:151], off offset:512
	v_lshl_add_u64 v[248:249], v[248:249], 0, s[60:61]
	global_store_dwordx4 v[248:249], v[152:155], off
	global_store_dwordx4 v[248:249], v[156:159], off offset:512
	v_lshlrev_b64 v[200:201], 12, v[168:169]
	v_lshl_add_u64 v[200:201], v[186:187], 0, v[200:201]
	global_load_dwordx4 v[144:147], v[200:201], off
	global_load_dwordx4 v[148:151], v[200:201], off offset:512
	v_lshl_add_u64 v[200:201], v[200:201], 0, s[60:61]
	global_load_dwordx4 v[152:155], v[200:201], off
	global_load_dwordx4 v[156:159], v[200:201], off offset:512
	v_lshlrev_b64 v[248:249], 12, v[172:173]
	v_lshl_add_u64 v[248:249], v[188:189], 0, v[248:249]
	s_waitcnt vmcnt(16)
	v_pk_fma_f32 v[202:203], v[60:61], v[140:141], v[202:203]
	v_pk_fma_f32 v[204:205], v[62:63], v[142:143], v[204:205]
	v_pk_fma_f32 v[206:207], v[48:49], v[132:133], v[206:207]
	v_pk_fma_f32 v[208:209], v[50:51], v[134:135], v[208:209]
	v_pk_fma_f32 v[210:211], v[56:57], v[140:141], v[210:211]
	v_pk_fma_f32 v[212:213], v[58:59], v[142:143], v[212:213]
	v_pk_fma_f32 v[214:215], v[40:41], v[132:133], v[214:215]
	v_pk_fma_f32 v[216:217], v[42:43], v[134:135], v[216:217]
	global_store_dwordx4 v[248:249], v[202:205], off
	global_store_dwordx4 v[248:249], v[206:209], off offset:512
	v_lshl_add_u64 v[248:249], v[248:249], 0, s[60:61]
	global_store_dwordx4 v[248:249], v[210:213], off
	global_store_dwordx4 v[248:249], v[214:217], off offset:512
	v_lshlrev_b64 v[200:201], 12, v[166:167]
	v_lshl_add_u64 v[200:201], v[186:187], 0, v[200:201]
	global_load_dwordx4 v[202:205], v[200:201], off
	global_load_dwordx4 v[206:209], v[200:201], off offset:512
	v_lshl_add_u64 v[200:201], v[200:201], 0, s[60:61]
	global_load_dwordx4 v[210:213], v[200:201], off
	global_load_dwordx4 v[214:217], v[200:201], off offset:512
	v_lshlrev_b64 v[248:249], 12, v[170:171]
	v_lshl_add_u64 v[248:249], v[188:189], 0, v[248:249]
	s_waitcnt vmcnt(16)
	v_pk_fma_f32 v[218:219], v[52:53], v[140:141], v[218:219]
	v_pk_fma_f32 v[220:221], v[54:55], v[142:143], v[220:221]
	v_pk_fma_f32 v[222:223], v[32:33], v[132:133], v[222:223]
	v_pk_fma_f32 v[224:225], v[34:35], v[134:135], v[224:225]
	v_pk_fma_f32 v[230:231], v[44:45], v[140:141], v[230:231]
	v_pk_fma_f32 v[232:233], v[46:47], v[142:143], v[232:233]
	v_pk_fma_f32 v[234:235], v[24:25], v[132:133], v[234:235]
	v_pk_fma_f32 v[236:237], v[26:27], v[134:135], v[236:237]
	global_store_dwordx4 v[248:249], v[218:221], off
	global_store_dwordx4 v[248:249], v[222:225], off offset:512
	v_lshl_add_u64 v[248:249], v[248:249], 0, s[60:61]
	global_store_dwordx4 v[248:249], v[230:233], off
	global_store_dwordx4 v[248:249], v[234:237], off offset:512
	v_lshlrev_b64 v[248:249], 12, v[168:169]
	v_lshl_add_u64 v[248:249], v[188:189], 0, v[248:249]
	s_waitcnt vmcnt(12)
	v_pk_fma_f32 v[144:145], v[36:37], v[140:141], v[144:145]
	v_pk_fma_f32 v[146:147], v[38:39], v[142:143], v[146:147]
	v_pk_fma_f32 v[148:149], v[16:17], v[132:133], v[148:149]
	v_pk_fma_f32 v[150:151], v[18:19], v[134:135], v[150:151]
	v_pk_fma_f32 v[152:153], v[28:29], v[140:141], v[152:153]
	v_pk_fma_f32 v[154:155], v[30:31], v[142:143], v[154:155]
	v_pk_fma_f32 v[156:157], v[8:9], v[132:133], v[156:157]
	v_pk_fma_f32 v[158:159], v[10:11], v[134:135], v[158:159]
	global_store_dwordx4 v[248:249], v[144:147], off
	global_store_dwordx4 v[248:249], v[148:151], off offset:512
	v_lshl_add_u64 v[248:249], v[248:249], 0, s[60:61]
	global_store_dwordx4 v[248:249], v[152:155], off
	global_store_dwordx4 v[248:249], v[156:159], off offset:512
	v_lshlrev_b64 v[248:249], 12, v[166:167]
	v_lshl_add_u64 v[248:249], v[188:189], 0, v[248:249]
	s_waitcnt vmcnt(8)
	v_pk_fma_f32 v[202:203], v[20:21], v[140:141], v[202:203]
	v_pk_fma_f32 v[204:205], v[22:23], v[142:143], v[204:205]
	v_pk_fma_f32 v[206:207], v[4:5], v[132:133], v[206:207]
	v_pk_fma_f32 v[208:209], v[6:7], v[134:135], v[208:209]
	v_pk_fma_f32 v[210:211], v[12:13], v[140:141], v[210:211]
	v_pk_fma_f32 v[212:213], v[14:15], v[142:143], v[212:213]
	v_pk_fma_f32 v[214:215], v[0:1], v[132:133], v[214:215]
	v_pk_fma_f32 v[216:217], v[2:3], v[134:135], v[216:217]
	global_store_dwordx4 v[248:249], v[202:205], off
	global_store_dwordx4 v[248:249], v[206:209], off offset:512
	v_lshl_add_u64 v[248:249], v[248:249], 0, s[60:61]
	global_store_dwordx4 v[248:249], v[210:213], off
	v_lshl_add_u64 v[184:185], v[248:249], 0, s[62:63]
	v_mov_b32_e32 v144, v214
	v_mov_b32_e32 v145, v215
	v_mov_b32_e32 v146, v216
	v_mov_b32_e32 v147, v217
	s_cbranch_execz .LBB0_71

; #define FOR_AI_M _Pragma("unroll") for (int ai = 0; ai < 2; ++ai) _Pragma("unroll") for (int m = 0; m < 4; ++m)
;     __device__ __forceinline__ void operator()(const f32x4 (&acc)[2][2][4][2], const Unit& u, int wr, int wc, int fr, int fq) const {
;         const int row0 = 256 * u.pm; const bool isctx = row0 >= NLAT; const int mb = isctx ? 4 : (row0 >> 13);
;         const float* bp = isctx ? base_ctx + (size_t)(row0 - NLAT) * 1024 : base_lat + (size_t)row0 * 1024;
;         float* op = isctx ? out_ctx + (size_t)(row0 - NLAT) * 1024 : out_lat + (size_t)row0 * 1024;
;         const float* mp = mod + mb * 6144 + moff;
;         f32x4 mv[2][2];
; #pragma unroll
;         for (int bj = 0; bj < 2; ++bj)
; #pragma unroll
;             for (int n = 0; n < 2; ++n) mv[bj][n] = *(const f32x4*)(mp + 256 * u.pn + 128 * bj + 32 * wc + 8 * fq + 4 * n);
;         const size_t cb0 = (size_t)256 * u.pn + 32 * wc + 8 * fq;
;         if (u.mode > 0) {
;             float* pp = part + (size_t)(u.mode - 1) * NCTX * 1024 + (size_t)(row0 - NLAT) * 1024;
;             FOR_AI_M {
;                 const size_t ro = (size_t)(128 * ai + 64 * wr + 16 * m + fr) * 1024 + cb0;
; #pragma unroll
;                 for (int bj = 0; bj < 2; ++bj)
; #pragma unroll
;                     for (int n = 0; n < 2; ++n) *(f32x4*)(pp + ro + 128 * bj + 4 * n) = mv[bj][n] * acc[ai][bj][m][n];
;             }
;             return;
;         }
;         f32x4 pre[2][2][2];
; #pragma unroll
;         for (int bj = 0; bj < 2; ++bj)
; #pragma unroll
;             for (int n = 0; n < 2; ++n) pre[0][bj][n] = *(const f32x4*)(bp + (size_t)(64 * wr + fr) * 1024 + cb0 + 128 * bj + 4 * n);
; #pragma unroll
;         for (int g = 0; g < 8; ++g) {
;             const int ai = g >> 2, m = g & 3;
;             const size_t ro = (size_t)(128 * ai + 64 * wr + 16 * m + fr) * 1024 + cb0;
;             if (g + 1 < 8) {
;                 const size_t rn = (size_t)(128 * ((g + 1) >> 2) + 64 * wr + 16 * ((g + 1) & 3) + fr) * 1024 + cb0;
; #pragma unroll
;                 for (int bj = 0; bj < 2; ++bj)
; #pragma unroll
;                     for (int n = 0; n < 2; ++n) pre[(g + 1) & 1][bj][n] = *(const f32x4*)(bp + rn + 128 * bj + 4 * n);
;             }
;             asm volatile("" ::: "memory");
.LBB0_201:
	s_min_i32 s21, s18, 0x80
	s_lshr_b32 s21, s21, 5
	s_mul_i32 s26, s21, 0x1800
	s_ashr_i32 s27, s26, 31
	s_lshl_b32 s24, s18, 8
	s_lshl_b64 s[26:27], s[26:27], 2
	v_readlane_b32 s8, v254, 44
	s_add_u32 s21, s8, s26
	v_readlane_b32 s8, v254, 46
	s_addc_u32 s25, s8, s27
	s_lshl_b32 s26, s20, 8
	s_ashr_i32 s27, s26, 31
	s_lshl_b64 s[26:27], s[26:27], 2
	s_add_u32 s21, s21, s26
	v_mov_b32_e32 v128, v198
	v_mov_b32_e32 v146, v197
	s_addc_u32 s25, s25, s27
	s_add_u32 s26, s21, s1
	v_lshlrev_b32_e32 v144, 3, v128
	s_addc_u32 s27, s25, 0
	v_ashrrev_i32_e32 v145, 31, v144
	v_lshl_add_u64 v[128:129], v[144:145], 2, s[26:27]
	s_mov_b64 s[26:27], 0x2000
	s_movk_i32 s8, 0x2000
	v_lshl_add_u64 v[130:131], v[128:129], 0, s[26:27]
	v_add_co_u32_e32 v128, vcc, s8, v128
	s_ashr_i32 s21, s20, 31
	s_nop 0
	v_addc_co_u32_e32 v129, vcc, 0, v129, vcc
	global_load_dwordx4 v[136:139], v[130:131], off offset:16
	global_load_dwordx4 v[132:135], v[130:131], off offset:512
	global_load_dwordx4 v[140:143], v[128:129], off
	s_nop 0
	global_load_dwordx4 v[128:131], v[130:131], off offset:528
	v_readlane_b32 s8, v254, 61
	s_lshl_b64 s[20:21], s[20:21], 8
	v_readlane_b32 s9, v254, 62
	s_or_b64 s[20:21], s[20:21], s[8:9]
	v_add_u32_e32 v180, s97, v146
	v_lshl_add_u64 v[182:183], s[20:21], 0, v[144:145]
	s_mov_b64 s[20:21], -1
	s_cmp_lt_i32 s94, 1
	v_ashrrev_i32_e32 v181, 31, v180
	v_add_u32_e32 v178, 16, v180
	v_add_u32_e32 v176, 32, v180
	v_add_u32_e32 v174, 48, v180
	v_add_u32_e32 v172, 0x80, v180
	v_add_u32_e32 v170, 0x90, v180
	v_add_u32_e32 v168, 0xa0, v180
	v_add_u32_e32 v166, 0xb0, v180
	v_readlane_b32 s95, v253, 26
	s_mov_b32 s64, 0x3f22f983
	s_cbranch_scc0 .LBB0_204
	s_add_i32 s20, s24, 0xffff8000
	s_ashr_i32 s21, s24, 31
	v_readlane_b32 s8, v251, 0
	s_cmpk_gt_i32 s18, 0x7f
	v_readlane_b32 s15, v251, 7
	v_readlane_b32 s8, v254, 49
	v_readlane_b32 s9, v251, 1
	v_readlane_b32 s14, v251, 6
	s_cselect_b32 s18, s8, s15
	v_readlane_b32 s8, v254, 47
	s_cselect_b32 s25, s8, s14
	v_readlane_b32 s8, v254, 22
	v_readlane_b32 s9, v254, 60
	s_cselect_b32 s21, 0, s21
	s_cselect_b32 s20, s20, s24
	s_cselect_b32 s28, s9, s8
	v_readlane_b32 s8, v254, 23
	v_readlane_b32 s9, v254, 53
	s_cselect_b32 s29, s9, s8
	s_lshl_b64 s[20:21], s[20:21], 12
	s_add_u32 s26, s25, s20
	s_addc_u32 s27, s18, s21
	s_add_u32 s20, s29, s20
	s_addc_u32 s21, s28, s21
	v_ashrrev_i32_e32 v181, 31, v180
	v_ashrrev_i32_e32 v179, 31, v178
	v_ashrrev_i32_e32 v177, 31, v176
	v_ashrrev_i32_e32 v175, 31, v174
	v_ashrrev_i32_e32 v173, 31, v172
	v_ashrrev_i32_e32 v171, 31, v170
	v_ashrrev_i32_e32 v169, 31, v168
	v_ashrrev_i32_e32 v167, 31, v166
	s_mov_b64 s[60:61], 0x8000
	s_mov_b64 s[62:63], -16
	s_add_i32 s58, s34, 0xc000
	v_mbcnt_lo_u32_b32 v248, -1, 0
	v_mbcnt_hi_u32_b32 v248, -1, v248
	v_lshrrev_b32_e32 v249, 4, v248
	v_and_b32_e32 v184, 7, v248
	v_xor_b32_e32 v184, v184, v249
	v_lshlrev_b32_e32 v184, 4, v184
	v_lshrrev_b32_e32 v185, 3, v248
	v_lshl_add_u32 v184, v185, 7, v184
	v_add_u32_e32 v201, s58, v184
	v_bfe_u32 v184, v248, 1, 2
	v_lshlrev_b32_e32 v185, 1, v249
	v_xor_b32_e32 v184, v184, v185
	v_lshlrev_b32_e32 v184, 4, v184
	v_and_b32_e32 v185, 7, v248
	v_lshl_add_u32 v184, v185, 7, v184
	v_bfe_u32 v185, v248, 3, 1
	v_lshl_add_u32 v184, v185, 13, v184
	v_add_u32_e32 v190, s58, v184
	v_xor_b32_e32 v191, 16, v190
	v_lshrrev_b32_e32 v184, 3, v248
	v_and_b32_e32 v185, 15, v248
	v_sub_u32_e32 v184, v184, v185
	v_lshlrev_b32_e32 v184, 12, v184
	v_and_b32_e32 v185, 7, v248
	v_lshl_add_u32 v184, v185, 4, v184
	v_lshlrev_b32_e32 v185, 5, v249
	v_sub_u32_e32 v184, v184, v185
	v_ashrrev_i32_e32 v185, 31, v184
	v_lshlrev_b64 v[186:187], 2, v[182:183]
	v_lshl_add_u64 v[186:187], v[184:185], 0, v[186:187]
	v_lshl_add_u64 v[188:189], s[26:27], 0, v[186:187]
	v_lshl_add_u64 v[186:187], s[20:21], 0, v[186:187]
	v_lshlrev_b64 v[184:185], 12, v[180:181]
	v_lshl_add_u64 v[184:185], v[186:187], 0, v[184:185]
	global_load_dwordx4 v[144:147], v[184:185], off
	global_load_dwordx4 v[148:151], v[184:185], off offset:512
	v_lshl_add_u64 v[184:185], v[184:185], 0, s[60:61]
	global_load_dwordx4 v[152:155], v[184:185], off
	global_load_dwordx4 v[156:159], v[184:185], off offset:512
	v_lshlrev_b64 v[184:185], 12, v[178:179]
	v_lshl_add_u64 v[184:185], v[186:187], 0, v[184:185]
	global_load_dwordx4 v[202:205], v[184:185], off
	global_load_dwordx4 v[206:209], v[184:185], off offset:512
	v_lshl_add_u64 v[184:185], v[184:185], 0, s[60:61]
	global_load_dwordx4 v[210:213], v[184:185], off
	global_load_dwordx4 v[214:217], v[184:185], off offset:512
	v_lshlrev_b64 v[184:185], 12, v[176:177]
	v_lshl_add_u64 v[184:185], v[186:187], 0, v[184:185]
	global_load_dwordx4 v[218:221], v[184:185], off
	global_load_dwordx4 v[222:225], v[184:185], off offset:512
	v_lshl_add_u64 v[184:185], v[184:185], 0, s[60:61]
	global_load_dwordx4 v[230:233], v[184:185], off
	global_load_dwordx4 v[234:237], v[184:185], off offset:512
	ds_write_b128 v190, v[124:127]
	ds_write_b128 v191, v[120:123]
	ds_read_b128 v[124:127], v201
	ds_read_b128 v[120:123], v201 offset:8192
	ds_write_b128 v190, v[116:119]
	ds_write_b128 v191, v[104:107]
	ds_read_b128 v[116:119], v201
	ds_read_b128 v[104:107], v201 offset:8192
	s_waitcnt lgkmcnt(2)
	ds_write_b128 v190, v[112:115]
	ds_write_b128 v191, v[108:111]
	ds_read_b128 v[112:115], v201
	ds_read_b128 v[108:111], v201 offset:8192
	ds_write_b128 v190, v[96:99]
	ds_write_b128 v191, v[88:91]
	ds_read_b128 v[96:99], v201
	ds_read_b128 v[88:91], v201 offset:8192
	s_waitcnt lgkmcnt(2)
	ds_write_b128 v190, v[100:103]
	ds_write_b128 v191, v[92:95]
	ds_read_b128 v[100:103], v201
	ds_read_b128 v[92:95], v201 offset:8192
	ds_write_b128 v190, v[80:83]
	ds_write_b128 v191, v[72:75]
	ds_read_b128 v[80:83], v201
	ds_read_b128 v[72:75], v201 offset:8192
	s_waitcnt lgkmcnt(2)
;     __device__ __forceinline__ void operator()(const f32x4 (&acc)[2][2][4][2], const Unit& u, int wr, int wc, int fr, int fq) const {
;     ...
;         for (int g = 0; g < 8; ++g) {
;             const int ai = g >> 2, m = g & 3;
;             const size_t ro = (size_t)(128 * ai + 64 * wr + 16 * m + fr) * 1024 + cb0;
;             if (g + 1 < 8) {
;                 const size_t rn = (size_t)(128 * ((g + 1) >> 2) + 64 * wr + 16 * ((g + 1) & 3) + fr) * 1024 + cb0;
; #pragma unroll
;                 for (int bj = 0; bj < 2; ++bj)
; #pragma unroll
;                     for (int n = 0; n < 2; ++n) pre[(g + 1) & 1][bj][n] = *(const f32x4*)(bp + rn + 128 * bj + 4 * n);
;             }
;             asm volatile("" ::: "memory");
; #pragma unroll
;             for (int bj = 0; bj < 2; ++bj)
; #pragma unroll
;                 for (int n = 0; n < 2; ++n) *(f32x4*)(op + ro + 128 * bj + 4 * n) = pre[g & 1][bj][n] + mv[bj][n] * acc[ai][bj][m][n];
;         }
	ds_write_b128 v190, v[84:87]
	ds_write_b128 v191, v[76:79]
	ds_read_b128 v[84:87], v201
	ds_read_b128 v[76:79], v201 offset:8192
	ds_write_b128 v190, v[68:71]
	ds_write_b128 v191, v[64:67]
	ds_read_b128 v[68:71], v201
	ds_read_b128 v[64:67], v201 offset:8192
	s_waitcnt lgkmcnt(2)
	ds_write_b128 v190, v[60:63]
	ds_write_b128 v191, v[56:59]
	ds_read_b128 v[60:63], v201
	ds_read_b128 v[56:59], v201 offset:8192
	ds_write_b128 v190, v[48:51]
	ds_write_b128 v191, v[40:43]
	ds_read_b128 v[48:51], v201
	ds_read_b128 v[40:43], v201 offset:8192
	s_waitcnt lgkmcnt(2)
	ds_write_b128 v190, v[52:55]
	ds_write_b128 v191, v[44:47]
	ds_read_b128 v[52:55], v201
	ds_read_b128 v[44:47], v201 offset:8192
	ds_write_b128 v190, v[32:35]
	ds_write_b128 v191, v[24:27]
	ds_read_b128 v[32:35], v201
	ds_read_b128 v[24:27], v201 offset:8192
	s_waitcnt lgkmcnt(2)
	ds_write_b128 v190, v[36:39]
	ds_write_b128 v191, v[28:31]
	ds_read_b128 v[36:39], v201
	ds_read_b128 v[28:31], v201 offset:8192
	ds_write_b128 v190, v[16:19]
	ds_write_b128 v191, v[8:11]
	ds_read_b128 v[16:19], v201
	ds_read_b128 v[8:11], v201 offset:8192
	s_waitcnt lgkmcnt(2)
	ds_write_b128 v190, v[20:23]
	ds_write_b128 v191, v[12:15]
	ds_read_b128 v[20:23], v201
	ds_read_b128 v[12:15], v201 offset:8192
	ds_write_b128 v190, v[4:7]
	ds_write_b128 v191, v[0:3]
	ds_read_b128 v[4:7], v201
	ds_read_b128 v[0:3], v201 offset:8192
	s_waitcnt lgkmcnt(2)
	s_waitcnt lgkmcnt(0)
	s_waitcnt vmcnt(8)
	v_mbcnt_lo_u32_b32 v185, -1, 0
	v_mbcnt_hi_u32_b32 v185, -1, v185
	v_lshrrev_b32_e32 v184, 4, v185
	v_lshl_add_u32 v184, v184, 5, s58
	v_and_b32_e32 v185, 7, v185
	v_lshl_add_u32 v185, v185, 4, s58
	ds_write_b128 v184, v[140:143]
	ds_write_b128 v184, v[136:139] offset:16
	ds_read_b128 v[140:143], v185
	ds_write_b128 v184, v[132:135]
	ds_write_b128 v184, v[128:131] offset:16
	ds_read_b128 v[132:135], v185
	s_waitcnt lgkmcnt(0)
	v_lshlrev_b64 v[248:249], 12, v[180:181]
	v_lshl_add_u64 v[248:249], v[188:189], 0, v[248:249]
	s_waitcnt vmcnt(8)
	v_pk_fma_f32 v[144:145], v[124:125], v[140:141], v[144:145]
	v_pk_fma_f32 v[146:147], v[126:127], v[142:143], v[146:147]
	v_pk_fma_f32 v[148:149], v[116:117], v[132:133], v[148:149]
	v_pk_fma_f32 v[150:151], v[118:119], v[134:135], v[150:151]
	v_pk_fma_f32 v[152:153], v[120:121], v[140:141], v[152:153]
	v_pk_fma_f32 v[154:155], v[122:123], v[142:143], v[154:155]
	v_pk_fma_f32 v[156:157], v[104:105], v[132:133], v[156:157]
	v_pk_fma_f32 v[158:159], v[106:107], v[134:135], v[158:159]
	global_store_dwordx4 v[248:249], v[144:147], off
	global_store_dwordx4 v[248:249], v[148:151], off offset:512
	v_lshl_add_u64 v[248:249], v[248:249], 0, s[60:61]
	global_store_dwordx4 v[248:249], v[152:155], off
	global_store_dwordx4 v[248:249], v[156:159], off offset:512
	v_lshlrev_b64 v[184:185], 12, v[174:175]
	v_lshl_add_u64 v[184:185], v[186:187], 0, v[184:185]
	global_load_dwordx4 v[144:147], v[184:185], off
	global_load_dwordx4 v[148:151], v[184:185], off offset:512
	v_lshl_add_u64 v[184:185], v[184:185], 0, s[60:61]
	global_load_dwordx4 v[152:155], v[184:185], off
	global_load_dwordx4 v[156:159], v[184:185], off offset:512
	v_lshlrev_b64 v[248:249], 12, v[178:179]
	v_lshl_add_u64 v[248:249], v[188:189], 0, v[248:249]
	s_waitcnt vmcnt(12)
	v_pk_fma_f32 v[202:203], v[112:113], v[140:141], v[202:203]
	v_pk_fma_f32 v[204:205], v[114:115], v[142:143], v[204:205]
	v_pk_fma_f32 v[206:207], v[96:97], v[132:133], v[206:207]
	v_pk_fma_f32 v[208:209], v[98:99], v[134:135], v[208:209]
	v_pk_fma_f32 v[210:211], v[108:109], v[140:141], v[210:211]
	v_pk_fma_f32 v[212:213], v[110:111], v[142:143], v[212:213]
	v_pk_fma_f32 v[214:215], v[88:89], v[132:133], v[214:215]
	v_pk_fma_f32 v[216:217], v[90:91], v[134:135], v[216:217]
	global_store_dwordx4 v[248:249], v[202:205], off
	global_store_dwordx4 v[248:249], v[206:209], off offset:512
	v_lshl_add_u64 v[248:249], v[248:249], 0, s[60:61]
	global_store_dwordx4 v[248:249], v[210:213], off
	global_store_dwordx4 v[248:249], v[214:217], off offset:512
	v_lshlrev_b64 v[184:185], 12, v[172:173]
	v_lshl_add_u64 v[184:185], v[186:187], 0, v[184:185]
	global_load_dwordx4 v[202:205], v[184:185], off
	global_load_dwordx4 v[206:209], v[184:185], off offset:512
	v_lshl_add_u64 v[184:185], v[184:185], 0, s[60:61]
	global_load_dwordx4 v[210:213], v[184:185], off
	global_load_dwordx4 v[214:217], v[184:185], off offset:512
	v_lshlrev_b64 v[248:249], 12, v[176:177]
	v_lshl_add_u64 v[248:249], v[188:189], 0, v[248:249]
	s_waitcnt vmcnt(16)
	v_pk_fma_f32 v[218:219], v[100:101], v[140:141], v[218:219]
	v_pk_fma_f32 v[220:221], v[102:103], v[142:143], v[220:221]
	v_pk_fma_f32 v[222:223], v[80:81], v[132:133], v[222:223]
	v_pk_fma_f32 v[224:225], v[82:83], v[134:135], v[224:225]
	v_pk_fma_f32 v[230:231], v[92:93], v[140:141], v[230:231]
	v_pk_fma_f32 v[232:233], v[94:95], v[142:143], v[232:233]
	v_pk_fma_f32 v[234:235], v[72:73], v[132:133], v[234:235]
	v_pk_fma_f32 v[236:237], v[74:75], v[134:135], v[236:237]
	global_store_dwordx4 v[248:249], v[218:221], off
	global_store_dwordx4 v[248:249], v[222:225], off offset:512
	v_lshl_add_u64 v[248:249], v[248:249], 0, s[60:61]
	global_store_dwordx4 v[248:249], v[230:233], off
	global_store_dwordx4 v[248:249], v[234:237], off offset:512
	v_lshlrev_b64 v[184:185], 12, v[170:171]
	v_lshl_add_u64 v[184:185], v[186:187], 0, v[184:185]
	global_load_dwordx4 v[218:221], v[184:185], off
	global_load_dwordx4 v[222:225], v[184:185], off offset:512
	v_lshl_add_u64 v[184:185], v[184:185], 0, s[60:61]
	global_load_dwordx4 v[230:233], v[184:185], off
	global_load_dwordx4 v[234:237], v[184:185], off offset:512
	v_lshlrev_b64 v[248:249], 12, v[174:175]
	v_lshl_add_u64 v[248:249], v[188:189], 0, v[248:249]
	s_waitcnt vmcnt(16)
;     __device__ __forceinline__ void operator()(const f32x4 (&acc)[2][2][4][2], const Unit& u, int wr, int wc, int fr, int fq) const {
;     ...
;         for (int g = 0; g < 8; ++g) {
;             const int ai = g >> 2, m = g & 3;
;             const size_t ro = (size_t)(128 * ai + 64 * wr + 16 * m + fr) * 1024 + cb0;
;             if (g + 1 < 8) {
;                 const size_t rn = (size_t)(128 * ((g + 1) >> 2) + 64 * wr + 16 * ((g + 1) & 3) + fr) * 1024 + cb0;
; #pragma unroll
;                 for (int bj = 0; bj < 2; ++bj)
; #pragma unroll
;                     for (int n = 0; n < 2; ++n) pre[(g + 1) & 1][bj][n] = *(const f32x4*)(bp + rn + 128 * bj + 4 * n);
;             }
;             asm volatile("" ::: "memory");
; #pragma unroll
;             for (int bj = 0; bj < 2; ++bj)
; #pragma unroll
;                 for (int n = 0; n < 2; ++n) *(f32x4*)(op + ro + 128 * bj + 4 * n) = pre[g & 1][bj][n] + mv[bj][n] * acc[ai][bj][m][n];
;         }
	v_pk_fma_f32 v[144:145], v[84:85], v[140:141], v[144:145]
	v_pk_fma_f32 v[146:147], v[86:87], v[142:143], v[146:147]
	v_pk_fma_f32 v[148:149], v[68:69], v[132:133], v[148:149]
	v_pk_fma_f32 v[150:151], v[70:71], v[134:135], v[150:151]
	v_pk_fma_f32 v[152:153], v[76:77], v[140:141], v[152:153]
	v_pk_fma_f32 v[154:155], v[78:79], v[142:143], v[154:155]
	v_pk_fma_f32 v[156:157], v[64:65], v[132:133], v[156:157]
	v_pk_fma_f32 v[158:159], v[66:67], v[134:135], v[158:159]
	global_store_dwordx4 v[248:249], v[144:147], off
	global_store_dwordx4 v[248:249], v[148:151], off offset:512
	v_lshl_add_u64 v[248:249], v[248:249], 0, s[60:61]
	global_store_dwordx4 v[248:249], v[152:155], off
	global_store_dwordx4 v[248:249], v[156:159], off offset:512
	v_lshlrev_b64 v[184:185], 12, v[168:169]
	v_lshl_add_u64 v[184:185], v[186:187], 0, v[184:185]
	global_load_dwordx4 v[144:147], v[184:185], off
	global_load_dwordx4 v[148:151], v[184:185], off offset:512
	v_lshl_add_u64 v[184:185], v[184:185], 0, s[60:61]
	global_load_dwordx4 v[152:155], v[184:185], off
	global_load_dwordx4 v[156:159], v[184:185], off offset:512
	v_lshlrev_b64 v[248:249], 12, v[172:173]
	v_lshl_add_u64 v[248:249], v[188:189], 0, v[248:249]
	s_waitcnt vmcnt(16)
	v_pk_fma_f32 v[202:203], v[60:61], v[140:141], v[202:203]
	v_pk_fma_f32 v[204:205], v[62:63], v[142:143], v[204:205]
	v_pk_fma_f32 v[206:207], v[48:49], v[132:133], v[206:207]
	v_pk_fma_f32 v[208:209], v[50:51], v[134:135], v[208:209]
	v_pk_fma_f32 v[210:211], v[56:57], v[140:141], v[210:211]
	v_pk_fma_f32 v[212:213], v[58:59], v[142:143], v[212:213]
	v_pk_fma_f32 v[214:215], v[40:41], v[132:133], v[214:215]
	v_pk_fma_f32 v[216:217], v[42:43], v[134:135], v[216:217]
	global_store_dwordx4 v[248:249], v[202:205], off
	global_store_dwordx4 v[248:249], v[206:209], off offset:512
	v_lshl_add_u64 v[248:249], v[248:249], 0, s[60:61]
	global_store_dwordx4 v[248:249], v[210:213], off
	global_store_dwordx4 v[248:249], v[214:217], off offset:512
	v_lshlrev_b64 v[184:185], 12, v[166:167]
	v_lshl_add_u64 v[184:185], v[186:187], 0, v[184:185]
	global_load_dwordx4 v[202:205], v[184:185], off
	global_load_dwordx4 v[206:209], v[184:185], off offset:512
	v_lshl_add_u64 v[184:185], v[184:185], 0, s[60:61]
	global_load_dwordx4 v[210:213], v[184:185], off
	global_load_dwordx4 v[214:217], v[184:185], off offset:512
	v_lshlrev_b64 v[248:249], 12, v[170:171]
	v_lshl_add_u64 v[248:249], v[188:189], 0, v[248:249]
	s_waitcnt vmcnt(16)
	v_pk_fma_f32 v[218:219], v[52:53], v[140:141], v[218:219]
	v_pk_fma_f32 v[220:221], v[54:55], v[142:143], v[220:221]
	v_pk_fma_f32 v[222:223], v[32:33], v[132:133], v[222:223]
	v_pk_fma_f32 v[224:225], v[34:35], v[134:135], v[224:225]
	v_pk_fma_f32 v[230:231], v[44:45], v[140:141], v[230:231]
	v_pk_fma_f32 v[232:233], v[46:47], v[142:143], v[232:233]
	v_pk_fma_f32 v[234:235], v[24:25], v[132:133], v[234:235]
	v_pk_fma_f32 v[236:237], v[26:27], v[134:135], v[236:237]
	global_store_dwordx4 v[248:249], v[218:221], off
	global_store_dwordx4 v[248:249], v[222:225], off offset:512
	v_lshl_add_u64 v[248:249], v[248:249], 0, s[60:61]
	global_store_dwordx4 v[248:249], v[230:233], off
	global_store_dwordx4 v[248:249], v[234:237], off offset:512
	v_lshlrev_b64 v[248:249], 12, v[168:169]
	v_lshl_add_u64 v[248:249], v[188:189], 0, v[248:249]
	s_waitcnt vmcnt(12)
	v_pk_fma_f32 v[144:145], v[36:37], v[140:141], v[144:145]
	v_pk_fma_f32 v[146:147], v[38:39], v[142:143], v[146:147]
	v_pk_fma_f32 v[148:149], v[16:17], v[132:133], v[148:149]
	v_pk_fma_f32 v[150:151], v[18:19], v[134:135], v[150:151]
	v_pk_fma_f32 v[152:153], v[28:29], v[140:141], v[152:153]
	v_pk_fma_f32 v[154:155], v[30:31], v[142:143], v[154:155]
	v_pk_fma_f32 v[156:157], v[8:9], v[132:133], v[156:157]
	v_pk_fma_f32 v[158:159], v[10:11], v[134:135], v[158:159]
	global_store_dwordx4 v[248:249], v[144:147], off
	global_store_dwordx4 v[248:249], v[148:151], off offset:512
	v_lshl_add_u64 v[248:249], v[248:249], 0, s[60:61]
	global_store_dwordx4 v[248:249], v[152:155], off
	global_store_dwordx4 v[248:249], v[156:159], off offset:512
	v_lshlrev_b64 v[248:249], 12, v[166:167]
	v_lshl_add_u64 v[248:249], v[188:189], 0, v[248:249]
	s_waitcnt vmcnt(8)
	v_pk_fma_f32 v[202:203], v[20:21], v[140:141], v[202:203]
	v_pk_fma_f32 v[204:205], v[22:23], v[142:143], v[204:205]
	v_pk_fma_f32 v[206:207], v[4:5], v[132:133], v[206:207]
	v_pk_fma_f32 v[208:209], v[6:7], v[134:135], v[208:209]
	v_pk_fma_f32 v[210:211], v[12:13], v[140:141], v[210:211]
	v_pk_fma_f32 v[212:213], v[14:15], v[142:143], v[212:213]
	v_pk_fma_f32 v[214:215], v[0:1], v[132:133], v[214:215]
	v_pk_fma_f32 v[216:217], v[2:3], v[134:135], v[216:217]
	global_store_dwordx4 v[248:249], v[202:205], off
	global_store_dwordx4 v[248:249], v[206:209], off offset:512
	v_lshl_add_u64 v[248:249], v[248:249], 0, s[60:61]
	global_store_dwordx4 v[248:249], v[210:213], off
	v_lshl_add_u64 v[148:149], v[248:249], 0, s[62:63]
	v_mov_b32_e32 v144, v214
	v_mov_b32_e32 v145, v215
	v_mov_b32_e32 v146, v216
	v_mov_b32_e32 v147, v217
	s_cbranch_execz .LBB0_205
